# adds E14 (band group 2 last step + drain skipped by waves 0-3) and E15 (FoX last step + drain skipped by fully-masked waves), stacked on E1,E4-E9,E11-E13b
# speedup vs baseline: 1.0162x; 1.0039x over previous
.LBB0_790:
	s_cmp_lt_i32 s21, 4
	s_cbranch_scc1 .Lxg_idle
	ds_read_b64_tr_b16 v[132:133], v174 offset:40960
	ds_read_b64_tr_b16 v[134:135], v174 offset:41472
	v_add_f32_e32 v48, v64, v65
	v_add_f32_e32 v48, v66, v48
	v_add_f32_e32 v48, v67, v48
	v_add_f32_e32 v48, v68, v48
	v_add_f32_e32 v80, v69, v48
	s_waitcnt lgkmcnt(9)
	v_mfma_f32_32x32x16_bf16 v[48:63], v[60:63], v[124:127], 0
	v_cvt_pk_bf16_f32 v104, v64, v65
	v_cvt_pk_bf16_f32 v105, v66, v67
	ds_read_b64_tr_b16 v[128:129], v174 offset:45056
	ds_read_b64_tr_b16 v[130:131], v174 offset:45568
	v_add_f32_e32 v64, v70, v80
	s_waitcnt lgkmcnt(10)
	v_mfma_f32_32x32x16_bf16 v[80:95], v[92:95], v[124:127], 0
	v_add_f32_e32 v64, v71, v64
	v_add_f32_e32 v64, v72, v64
	v_add_f32_e32 v100, v73, v64
	v_cvt_pk_bf16_f32 v106, v68, v69
	v_cvt_pk_bf16_f32 v107, v70, v71
	ds_read_b64_tr_b16 v[64:65], v174 offset:41984
	ds_read_b64_tr_b16 v[66:67], v174 offset:42496
	s_waitcnt lgkmcnt(11)
	v_mfma_f32_32x32x16_bf16 v[48:63], v[156:159], v[120:123], v[48:63]
	v_add_f32_e32 v68, v74, v100
	v_add_f32_e32 v68, v75, v68
	v_add_f32_e32 v68, v76, v68
	v_add_f32_e32 v112, v77, v68
	v_cvt_pk_bf16_f32 v100, v72, v73
	v_cvt_pk_bf16_f32 v101, v74, v75
	ds_read_b64_tr_b16 v[68:69], v174 offset:46080
	ds_read_b64_tr_b16 v[70:71], v174 offset:46592
	s_waitcnt lgkmcnt(12)
	v_mfma_f32_32x32x16_bf16 v[80:95], v[152:155], v[120:123], v[80:95]
	v_add_f32_e32 v72, v78, v112
	v_add_f32_e32 v72, v79, v72
	v_add_f32_e32 v72, v32, v72
	v_add_f32_e32 v112, v33, v72
	v_cvt_pk_bf16_f32 v102, v76, v77
	v_cvt_pk_bf16_f32 v103, v78, v79
	ds_read_b64_tr_b16 v[72:73], v174 offset:43008
	ds_read_b64_tr_b16 v[74:75], v174 offset:43520
	s_waitcnt lgkmcnt(13)
	v_mfma_f32_32x32x16_bf16 v[48:63], v[148:151], v[108:111], v[48:63]
	v_add_f32_e32 v76, v34, v112
	v_add_f32_e32 v76, v35, v76
	v_add_f32_e32 v76, v36, v76
	v_add_f32_e32 v76, v37, v76
	v_cvt_pk_bf16_f32 v112, v32, v33
	v_cvt_pk_bf16_f32 v113, v34, v35
	ds_read_b64_tr_b16 v[32:33], v174 offset:47104
	ds_read_b64_tr_b16 v[34:35], v174 offset:47616
	s_waitcnt lgkmcnt(14)
	v_mfma_f32_32x32x16_bf16 v[80:95], v[144:147], v[108:111], v[80:95]
	v_add_f32_e32 v76, v38, v76
	v_add_f32_e32 v76, v39, v76
	v_add_f32_e32 v76, v40, v76
	v_add_f32_e32 v76, v41, v76
	v_cvt_pk_bf16_f32 v114, v36, v37
	v_cvt_pk_bf16_f32 v115, v38, v39
	ds_read_b64_tr_b16 v[36:37], v174 offset:44032
	ds_read_b64_tr_b16 v[38:39], v174 offset:44544
	s_waitcnt lgkmcnt(14)
	v_mfma_f32_32x32x16_bf16 v[48:63], v[140:143], v[96:99], v[48:63]
	v_add_f32_e32 v76, v42, v76
	v_add_f32_e32 v76, v43, v76
	v_add_f32_e32 v76, v44, v76
	v_add_f32_e32 v76, v45, v76
	v_cvt_pk_bf16_f32 v116, v40, v41
	v_cvt_pk_bf16_f32 v117, v42, v43
	ds_read_b64_tr_b16 v[40:41], v174 offset:48128
	ds_read_b64_tr_b16 v[42:43], v174 offset:48640
	v_mfma_f32_32x32x16_bf16 v[80:95], v[136:139], v[96:99], v[80:95]
	v_add_f32_e32 v76, v46, v76
	v_add_f32_e32 v76, v47, v76
	v_add_f32_e32 v76, 0, v76
	v_cvt_pk_bf16_f32 v118, v44, v45
	v_cvt_pk_bf16_f32 v119, v46, v47
	v_or_b32_e32 v142, 0xc0, v167
	s_cmp_gt_i32 s21, 7
	v_or_b32_e32 v143, 0xe0, v167
	v_or_b32_e32 v141, 0xe1, v167
	v_or_b32_e32 v139, 0xc2, v167
	v_or_b32_e32 v140, 0xe2, v167
	v_or_b32_e32 v137, 0xc3, v167
	v_or_b32_e32 v138, 0xe3, v167
	v_or_b32_e32 v127, 0xc8, v167
	v_or_b32_e32 v136, 0xe8, v167
	v_or_b32_e32 v125, 0xc9, v167
	v_or_b32_e32 v126, 0xe9, v167
	v_or_b32_e32 v123, 0xca, v167
	v_or_b32_e32 v124, 0xea, v167
	v_or_b32_e32 v121, 0xcb, v167
	v_or_b32_e32 v122, 0xeb, v167
	v_or_b32_e32 v111, 0xd0, v167
	v_or_b32_e32 v120, 0xf0, v167
	v_or_b32_e32 v109, 0xd1, v167
	v_or_b32_e32 v110, 0xf1, v167
	v_or_b32_e32 v99, 0xd2, v167
	v_or_b32_e32 v108, 0xf2, v167
	v_or_b32_e32 v97, 0xd3, v167
	v_or_b32_e32 v98, 0xf3, v167
	v_or_b32_e32 v79, 0xd8, v167
	v_or_b32_e32 v96, 0xf8, v167
	v_or_b32_e32 v77, 0xd9, v167
	v_or_b32_e32 v78, 0xf9, v167
	v_or_b32_e32 v46, 0xda, v167
	v_or_b32_e32 v47, 0xfa, v167
	v_or_b32_e32 v44, 0xdb, v167
	v_or_b32_e32 v45, 0xfb, v167
	s_cbranch_scc1 .LBB0_794
	v_cmp_le_i32_e64 s[0:1], v143, v169
	v_cmp_le_i32_e64 s[38:39], v141, v169
	v_cmp_le_i32_e64 s[40:41], v140, v169
	v_cmp_le_i32_e64 s[42:43], v138, v169
	v_cmp_le_i32_e64 s[44:45], v136, v169
	v_cmp_le_i32_e64 s[46:47], v126, v169
	v_cmp_le_i32_e64 s[50:51], v124, v169
	v_cmp_le_i32_e64 s[52:53], v122, v169
	v_cmp_le_i32_e64 s[54:55], v120, v169
	v_cmp_le_i32_e64 s[56:57], v110, v169
	v_cmp_le_i32_e64 s[58:59], v108, v169
	v_cmp_le_i32_e64 s[60:61], v98, v169
	v_cmp_le_i32_e64 s[62:63], v96, v169
	v_cmp_le_i32_e64 s[64:65], v78, v169
	v_cmp_le_i32_e64 s[66:67], v47, v169
	v_cmp_le_i32_e32 vcc, v142, v169
	v_cndmask_b32_e64 v80, v240, v80, s[0:1]
	v_cmp_lt_i32_e64 s[0:1], v142, v169
	v_cndmask_b32_e64 v81, v240, v81, s[38:39]
	v_cmp_le_i32_e64 s[38:39], v139, v169
	v_cndmask_b32_e64 v82, v240, v82, s[40:41]
	v_cmp_le_i32_e64 s[40:41], v137, v169
	v_cndmask_b32_e64 v83, v240, v83, s[42:43]
	v_cmp_le_i32_e64 s[42:43], v127, v169
	v_cndmask_b32_e64 v84, v240, v84, s[44:45]
	v_cmp_le_i32_e64 s[44:45], v125, v169
	v_cndmask_b32_e64 v85, v240, v85, s[46:47]
	v_cmp_le_i32_e64 s[46:47], v123, v169
	v_cndmask_b32_e64 v86, v240, v86, s[50:51]
	v_cmp_le_i32_e64 s[50:51], v121, v169
	v_cndmask_b32_e64 v87, v240, v87, s[52:53]
	v_cmp_le_i32_e64 s[52:53], v111, v169
	v_cndmask_b32_e64 v88, v240, v88, s[54:55]
	v_cmp_le_i32_e64 s[54:55], v109, v169
	v_cndmask_b32_e64 v89, v240, v89, s[56:57]
	v_cmp_le_i32_e64 s[56:57], v99, v169
	v_cndmask_b32_e64 v90, v240, v90, s[58:59]
	v_cmp_le_i32_e64 s[58:59], v97, v169
	v_cndmask_b32_e64 v91, v240, v91, s[60:61]
	v_cmp_le_i32_e64 s[60:61], v79, v169
	v_cndmask_b32_e64 v92, v240, v92, s[62:63]
	v_cmp_le_i32_e64 s[62:63], v77, v169
	v_cndmask_b32_e64 v93, v240, v93, s[64:65]
	v_cmp_le_i32_e64 s[64:65], v46, v169
	v_cndmask_b32_e64 v94, v240, v94, s[66:67]
	v_cmp_le_i32_e64 s[66:67], v44, v169
	v_cmp_gt_i32_e64 s[68:69], v45, v169
	s_and_saveexec_b64 s[2:3], s[68:69]
	s_mov_b32 s12, 0xff800000
	v_mov_b32_e32 v95, s12
	s_or_b64 exec, exec, s[2:3]
	v_cndmask_b32_e64 v49, v240, v49, s[0:1]
	v_cndmask_b32_e32 v48, v240, v48, vcc
	v_cndmask_b32_e64 v50, v240, v50, s[38:39]
	v_cndmask_b32_e64 v51, v240, v51, s[40:41]
	v_cndmask_b32_e64 v52, v240, v52, s[42:43]
	v_cndmask_b32_e64 v53, v240, v53, s[44:45]
	v_cndmask_b32_e64 v54, v240, v54, s[46:47]
	v_cndmask_b32_e64 v55, v240, v55, s[50:51]
	v_cndmask_b32_e64 v56, v240, v56, s[52:53]
	v_cndmask_b32_e64 v57, v240, v57, s[54:55]
	v_cndmask_b32_e64 v58, v240, v58, s[56:57]
	v_cndmask_b32_e64 v59, v240, v59, s[58:59]
	v_cndmask_b32_e64 v60, v240, v60, s[60:61]
	v_cndmask_b32_e64 v61, v240, v61, s[62:63]
	v_cndmask_b32_e64 v62, v240, v62, s[64:65]
	v_cndmask_b32_e64 v63, v240, v63, s[66:67]

.Lxg_join:
	v_mov_b32_e32 v33, v32
	s_nop 1
	v_permlane32_swap_b32_e32 v32, v33
	v_cmp_gt_u32_e32 vcc, 32, v164
	s_and_saveexec_b64 s[0:1], vcc
	s_cbranch_execz .LBB0_704
	v_add_f32_e32 v32, v32, v33
	v_log_f32_e32 v33, v32
	v_lshl_add_u32 v34, v165, 2, s2
	v_add_u32_e32 v34, 0xc000, v34
	v_add_f32_e32 v33, 0, v33
	ds_write2_b32 v34, v33, v32 offset1:32
	s_branch .LBB0_704
.Lxg_idle:
	s_and_b32 s0, s20, 0x3fffffc0
	s_lshl_b32 s0, s0, 2
	s_add_i32 s2, s0, 0
	v_add_f32_e32 v32, v173, v175
	s_branch .Lxg_join

.LBB0_1028:
	s_lshl_b32 s0, s41, 6
	s_sub_i32 s0, s0, 0x9f
	s_cmp_gt_i32 s0, s21
	s_cbranch_scc1 .Lxh_idle
	s_add_i32 s41, s41, -1
	s_lshl_b32 s0, s41, 8
	s_add_i32 s92, s92, s0
	v_lshl_add_u32 v33, v218, 2, s92
	ds_read_b128 v[34:37], v33
	ds_read_b128 v[38:41], v33 offset:32
	ds_read_b128 v[42:45], v33 offset:64
	ds_read_b128 v[80:83], v33 offset:96
	ds_read_b128 v[96:99], v33 offset:128
	ds_read_b128 v[100:103], v33 offset:160
	ds_read_b128 v[104:107], v33 offset:192
	ds_read_b128 v[108:111], v33 offset:224
	s_waitcnt lgkmcnt(4)
	v_sub_f32_e32 v95, v222, v83
	v_sub_f32_e32 v94, v222, v82
	v_sub_f32_e32 v93, v222, v81
	v_sub_f32_e32 v92, v222, v80
	v_sub_f32_e32 v91, v222, v45
	v_sub_f32_e32 v90, v222, v44
	v_sub_f32_e32 v89, v222, v43
	v_sub_f32_e32 v88, v222, v42
	v_sub_f32_e32 v87, v222, v41
	v_sub_f32_e32 v86, v222, v40
	v_sub_f32_e32 v85, v222, v39
	v_sub_f32_e32 v84, v222, v38
	v_sub_f32_e32 v83, v222, v37
	v_sub_f32_e32 v82, v222, v36
	v_sub_f32_e32 v81, v222, v35
	v_sub_f32_e32 v80, v222, v34
	s_waitcnt lgkmcnt(0)
	v_sub_f32_e32 v111, v222, v111
	v_sub_f32_e32 v110, v222, v110
	v_sub_f32_e32 v109, v222, v109
	v_sub_f32_e32 v108, v222, v108
	v_sub_f32_e32 v107, v222, v107
	v_sub_f32_e32 v106, v222, v106
	v_sub_f32_e32 v105, v222, v105
	v_sub_f32_e32 v104, v222, v104
	v_sub_f32_e32 v103, v222, v103
	v_sub_f32_e32 v102, v222, v102
	v_sub_f32_e32 v101, v222, v101
	v_sub_f32_e32 v100, v222, v100
	v_sub_f32_e32 v99, v222, v99
	v_sub_f32_e32 v98, v222, v98
	v_sub_f32_e32 v97, v222, v97
	v_sub_f32_e32 v96, v222, v96
	v_add_u32_e32 v33, s22, v224
	ds_read_b64_tr_b16 v[34:35], v33 offset:24576
	ds_read_b64_tr_b16 v[36:37], v33 offset:25088
	v_mfma_f32_32x32x16_bf16 v[80:95], v[172:175], v[124:127], v[80:95]
	v_add_f32_e32 v38, v64, v65
	v_add_f32_e32 v38, v66, v38
	v_add_f32_e32 v38, v67, v38
	v_add_f32_e32 v38, v68, v38
	v_add_f32_e32 v42, v69, v38
	v_cvt_pk_bf16_f32 v140, v64, v65
	v_cvt_pk_bf16_f32 v141, v66, v67
	ds_read_b64_tr_b16 v[38:39], v33 offset:28672
	ds_read_b64_tr_b16 v[40:41], v33 offset:29184
	v_mfma_f32_32x32x16_bf16 v[96:111], v[168:171], v[124:127], v[96:111]
	v_add_f32_e32 v42, v70, v42
	v_add_f32_e32 v42, v71, v42
	v_add_f32_e32 v42, v72, v42
	v_add_f32_e32 v46, v73, v42
	v_cvt_pk_bf16_f32 v142, v68, v69
	v_cvt_pk_bf16_f32 v143, v70, v71
	ds_read_b64_tr_b16 v[42:43], v33 offset:25600
	ds_read_b64_tr_b16 v[44:45], v33 offset:26112
	v_mfma_f32_32x32x16_bf16 v[80:95], v[164:167], v[120:123], v[80:95]
	v_add_f32_e32 v46, v74, v46
	v_add_f32_e32 v46, v75, v46
	v_add_f32_e32 v46, v76, v46
	v_add_f32_e32 v46, v77, v46
	v_cvt_pk_bf16_f32 v136, v72, v73
	v_cvt_pk_bf16_f32 v137, v74, v75
	ds_read_b64_tr_b16 v[64:65], v33 offset:29696
	ds_read_b64_tr_b16 v[66:67], v33 offset:30208
	v_mfma_f32_32x32x16_bf16 v[96:111], v[160:163], v[120:123], v[96:111]
	v_add_f32_e32 v46, v78, v46
	v_add_f32_e32 v46, v79, v46
	v_add_f32_e32 v46, v48, v46
	v_add_f32_e32 v46, v49, v46
	v_cvt_pk_bf16_f32 v138, v76, v77
	v_cvt_pk_bf16_f32 v139, v78, v79
	ds_read_b64_tr_b16 v[68:69], v33 offset:26624
	ds_read_b64_tr_b16 v[70:71], v33 offset:27136
	v_mfma_f32_32x32x16_bf16 v[80:95], v[156:159], v[116:119], v[80:95]
	v_add_f32_e32 v46, v50, v46
	v_add_f32_e32 v46, v51, v46
	v_add_f32_e32 v46, v52, v46
	v_add_f32_e32 v72, v53, v46
	v_cvt_pk_bf16_f32 v132, v48, v49
	v_cvt_pk_bf16_f32 v133, v50, v51
	ds_read_b64_tr_b16 v[46:47], v33 offset:30720
	ds_read_b64_tr_b16 v[48:49], v33 offset:31232
	v_mfma_f32_32x32x16_bf16 v[96:111], v[152:155], v[116:119], v[96:111]
	v_add_f32_e32 v50, v54, v72
	v_add_f32_e32 v50, v55, v50
	v_add_f32_e32 v50, v56, v50
	v_add_f32_e32 v72, v57, v50
	v_cvt_pk_bf16_f32 v134, v52, v53
	v_cvt_pk_bf16_f32 v135, v54, v55
	ds_read_b64_tr_b16 v[50:51], v33 offset:27648
	ds_read_b64_tr_b16 v[52:53], v33 offset:28160
	v_mfma_f32_32x32x16_bf16 v[80:95], v[148:151], v[112:115], v[80:95]
	v_add_f32_e32 v54, v58, v72
	v_add_f32_e32 v54, v59, v54
	v_add_f32_e32 v54, v60, v54
	v_add_f32_e32 v72, v61, v54
	v_cvt_pk_bf16_f32 v128, v56, v57
	v_cvt_pk_bf16_f32 v129, v58, v59
	ds_read_b64_tr_b16 v[54:55], v33 offset:31744
	ds_read_b64_tr_b16 v[56:57], v33 offset:32256
	v_mfma_f32_32x32x16_bf16 v[96:111], v[144:147], v[112:115], v[96:111]
	v_add_f32_e32 v33, v62, v72
	v_add_f32_e32 v33, v63, v33
	v_add_f32_e32 v33, 0, v33
	v_cvt_pk_bf16_f32 v130, v60, v61
	v_cvt_pk_bf16_f32 v131, v62, v63
	s_lshl_b32 s0, s41, 6
	s_or_b32 s1, s0, 63
	s_cmp_le_i32 s1, s21
	s_cbranch_scc1 .LBB0_1032
	v_or_b32_e32 v58, s0, v218
	v_or_b32_e32 v59, 32, v58
	v_cmp_le_i32_e64 s[0:1], v59, v220
	v_or_b32_e32 v59, 33, v58
	v_cmp_le_i32_e64 s[42:43], v59, v220
	v_or_b32_e32 v59, 2, v58
	v_cmp_le_i32_e32 vcc, v58, v220
	v_cndmask_b32_e64 v97, v240, v97, s[42:43]
	v_cmp_le_i32_e64 s[42:43], v59, v220
	v_or_b32_e32 v59, 34, v58
	v_cmp_le_i32_e64 s[44:45], v59, v220
	v_or_b32_e32 v59, 3, v58
	v_cndmask_b32_e64 v96, v240, v96, s[0:1]
	v_cndmask_b32_e64 v98, v240, v98, s[44:45]
	v_cmp_le_i32_e64 s[44:45], v59, v220
	v_or_b32_e32 v59, 35, v58
	v_cmp_le_i32_e64 s[46:47], v59, v220
	v_or_b32_e32 v59, 8, v58
	v_cmp_lt_i32_e64 s[0:1], v58, v220
	v_cndmask_b32_e64 v99, v240, v99, s[46:47]
	v_cmp_le_i32_e64 s[46:47], v59, v220
	v_or_b32_e32 v59, 40, v58
	v_cmp_le_i32_e64 s[50:51], v59, v220
	v_or_b32_e32 v59, 9, v58
	s_nop 0
	v_cndmask_b32_e64 v100, v240, v100, s[50:51]
	v_cmp_le_i32_e64 s[50:51], v59, v220
	v_or_b32_e32 v59, 41, v58
	v_cmp_le_i32_e64 s[52:53], v59, v220
	v_or_b32_e32 v59, 10, v58
	s_nop 0
	v_cndmask_b32_e64 v101, v240, v101, s[52:53]
	v_cmp_le_i32_e64 s[52:53], v59, v220
	v_or_b32_e32 v59, 42, v58
	v_cmp_le_i32_e64 s[54:55], v59, v220
	v_or_b32_e32 v59, 11, v58
	s_nop 0
	v_cndmask_b32_e64 v102, v240, v102, s[54:55]
	v_cmp_le_i32_e64 s[54:55], v59, v220
	v_or_b32_e32 v59, 43, v58
	v_cmp_le_i32_e64 s[56:57], v59, v220
	v_or_b32_e32 v59, 16, v58
	s_nop 0
	v_cndmask_b32_e64 v103, v240, v103, s[56:57]
	v_cmp_le_i32_e64 s[56:57], v59, v220
	v_or_b32_e32 v59, 48, v58
	v_cmp_le_i32_e64 s[58:59], v59, v220
	v_or_b32_e32 v59, 17, v58
	s_nop 0
	v_cndmask_b32_e64 v104, v240, v104, s[58:59]
	v_cmp_le_i32_e64 s[58:59], v59, v220
	v_or_b32_e32 v59, 49, v58
	v_cmp_le_i32_e64 s[60:61], v59, v220
	v_or_b32_e32 v59, 18, v58
	s_nop 0
	v_cndmask_b32_e64 v105, v240, v105, s[60:61]
	v_cmp_le_i32_e64 s[60:61], v59, v220
	v_or_b32_e32 v59, 50, v58
	v_cmp_le_i32_e64 s[62:63], v59, v220
	v_or_b32_e32 v59, 19, v58
	s_nop 0
	v_cndmask_b32_e64 v106, v240, v106, s[62:63]
	v_cmp_le_i32_e64 s[62:63], v59, v220
	v_or_b32_e32 v59, 51, v58
	v_cmp_le_i32_e64 s[64:65], v59, v220
	v_or_b32_e32 v59, 24, v58
	s_nop 0
	v_cndmask_b32_e64 v107, v240, v107, s[64:65]
	v_cmp_le_i32_e64 s[64:65], v59, v220
	v_or_b32_e32 v59, 56, v58
	v_cmp_le_i32_e64 s[66:67], v59, v220
	v_or_b32_e32 v59, 25, v58
	s_nop 0
	v_cndmask_b32_e64 v108, v240, v108, s[66:67]
	v_cmp_le_i32_e64 s[66:67], v59, v220
	v_or_b32_e32 v59, 57, v58
	v_cmp_le_i32_e64 s[68:69], v59, v220
	v_or_b32_e32 v59, 26, v58
	s_nop 0
	v_cndmask_b32_e64 v109, v240, v109, s[68:69]
	v_cmp_le_i32_e64 s[68:69], v59, v220
	v_or_b32_e32 v59, 58, v58
	v_cmp_le_i32_e64 s[70:71], v59, v220
	v_or_b32_e32 v59, 27, v58
	v_or_b32_e32 v58, 59, v58
	v_cndmask_b32_e64 v110, v240, v110, s[70:71]
	v_cmp_le_i32_e64 s[70:71], v59, v220
	v_cmp_gt_i32_e64 s[72:73], v58, v220
	s_and_saveexec_b64 s[2:3], s[72:73]
	s_mov_b32 s6, 0xff800000
	v_mov_b32_e32 v111, s6
	s_or_b64 exec, exec, s[2:3]
	v_cndmask_b32_e64 v81, v240, v81, s[0:1]
	v_cndmask_b32_e32 v80, v240, v80, vcc
	v_cndmask_b32_e64 v82, v240, v82, s[42:43]
	v_cndmask_b32_e64 v83, v240, v83, s[44:45]
	v_cndmask_b32_e64 v84, v240, v84, s[46:47]
	v_cndmask_b32_e64 v85, v240, v85, s[50:51]
	v_cndmask_b32_e64 v86, v240, v86, s[52:53]
	v_cndmask_b32_e64 v87, v240, v87, s[54:55]
	v_cndmask_b32_e64 v88, v240, v88, s[56:57]
	v_cndmask_b32_e64 v89, v240, v89, s[58:59]
	v_cndmask_b32_e64 v90, v240, v90, s[60:61]
	v_cndmask_b32_e64 v91, v240, v91, s[62:63]
	v_cndmask_b32_e64 v92, v240, v92, s[64:65]
	v_cndmask_b32_e64 v93, v240, v93, s[66:67]
	v_cndmask_b32_e64 v94, v240, v94, s[68:69]
	v_cndmask_b32_e64 v95, v240, v95, s[70:71]

.Lxh_join:
	v_mov_b32_e32 v33, v32
	s_nop 1
	v_permlane32_swap_b32_e32 v32, v33
	v_cmp_gt_u32_e32 vcc, 32, v215
	s_and_saveexec_b64 s[0:1], vcc
	s_cbranch_execz .LBB0_857
	v_add_f32_e32 v32, v32, v33
	v_lshl_add_u32 v33, v216, 2, s2
	ds_write_b32 v33, v32 offset:49280
	s_branch .LBB0_857
.Lxh_idle:
	s_add_i32 s41, s41, -1
	s_lshl_b32 s0, s41, 8
	s_add_i32 s92, s92, s0
	s_and_b32 s0, s15, 0x3fffffc0
	s_lshl_b32 s0, s0, 2
	s_add_i32 s2, s0, 0
	s_branch .Lxh_join
